# EpiMix per-row ssq loads batched; final_norm and rope_pass: rowsq/pos loads issued with the data loads so later items do not wait behind earlier stores
# speedup vs baseline: 1.1140x; 1.0032x over previous
.LBB0_23:
	v_and_b32_e32 v0, 0x3fc, v30
	v_readlane_b32 s8, v253, 5
	v_ashrrev_i32_e32 v26, 8, v18
	v_lshlrev_b32_e32 v0, 2, v0
	v_readlane_b32 s14, v253, 11
	v_readlane_b32 s15, v253, 12
	v_ashrrev_i32_e32 v27, 31, v26
	v_lshlrev_b64 v[24:25], 12, v[26:27]
	v_lshl_add_u64 v[28:29], s[14:15], 0, v[0:1]
	v_lshl_add_u64 v[14:15], v[28:29], 0, v[24:25]
	global_load_dwordx4 v[14:17], v[14:15], off
	v_add_u32_e32 v31, s6, v18
	v_ashrrev_i32_e32 v20, 8, v31
	v_cmp_gt_i32_e32 vcc, s19, v31
	v_ashrrev_i32_e32 v21, 31, v20
	v_readlane_b32 s9, v253, 6
	v_readlane_b32 s10, v253, 7
	v_readlane_b32 s11, v253, 8
	v_readlane_b32 s12, v253, 9
	v_readlane_b32 s13, v253, 10
	s_and_saveexec_b64 s[0:1], vcc
	s_cbranch_execz .LBB0_25
	v_lshlrev_b64 v[2:3], 12, v[20:21]
	v_lshl_add_u64 v[2:3], v[28:29], 0, v[2:3]
	global_load_dwordx4 v[2:5], v[2:3], off
	v_lshl_add_u64 v[36:37], v[20:21], 2, s[20:21]
	global_load_dword v41, v[36:37], off
.LBB0_25:
	s_or_b64 exec, exec, s[0:1]
	v_readlane_b32 s0, v254, 29
	s_nop 1
	v_add_u32_e32 v19, s0, v18
	v_ashrrev_i32_e32 v22, 8, v19
	v_cmp_gt_i32_e64 s[0:1], s19, v19
	v_ashrrev_i32_e32 v23, 31, v22
	s_and_saveexec_b64 s[6:7], s[0:1]
	s_cbranch_execz .LBB0_27
	v_lshlrev_b64 v[6:7], 12, v[22:23]
	v_lshl_add_u64 v[6:7], v[28:29], 0, v[6:7]
	global_load_dwordx4 v[6:9], v[6:7], off
	v_lshl_add_u64 v[36:37], v[22:23], 2, s[20:21]
	global_load_dword v42, v[36:37], off
.LBB0_27:
	s_or_b64 exec, exec, s[6:7]
	v_readlane_b32 s6, v253, 51
	s_nop 1
	v_add_u32_e32 v18, s6, v18
	v_cmp_gt_i32_e64 s[6:7], s19, v18
	v_ashrrev_i32_e32 v18, 8, v18
	v_ashrrev_i32_e32 v19, 31, v18
	s_and_saveexec_b64 s[8:9], s[6:7]
	s_cbranch_execz .LBB0_29
	v_lshlrev_b64 v[10:11], 12, v[18:19]
	v_lshl_add_u64 v[10:11], v[28:29], 0, v[10:11]
	global_load_dwordx4 v[10:13], v[10:11], off
	v_lshl_add_u64 v[36:37], v[18:19], 2, s[20:21]
	global_load_dword v43, v[36:37], off
.LBB0_29:
	s_or_b64 exec, exec, s[8:9]
	v_lshl_add_u64 v[26:27], v[26:27], 2, s[20:21]
	global_load_dword v26, v[26:27], off
	v_readlane_b32 s8, v253, 5
	v_readlane_b32 s12, v253, 9
	v_readlane_b32 s13, v253, 10
	v_readlane_b32 s9, v253, 6
	s_mov_b32 s8, 0x800000
	v_readlane_b32 s14, v253, 11
	v_readlane_b32 s15, v253, 12
	v_readlane_b32 s10, v253, 7
	global_load_dwordx4 v[32:35], v0, s[12:13]
	v_lshl_add_u64 v[24:25], s[14:15], 0, v[24:25]
	v_lshl_add_u64 v[24:25], v[24:25], 0, v[0:1]
	v_readlane_b32 s11, v253, 8
	s_waitcnt vmcnt(1)
	v_fmamk_f32 v26, v26, 0x3a800000, v219
	v_mul_f32_e32 v27, 0x4b800000, v26
	v_cmp_gt_f32_e64 s[8:9], s8, v26
	s_nop 1
	v_cndmask_b32_e64 v26, v26, v27, s[8:9]
	v_rsq_f32_e32 v28, v26
	v_lshl_add_u64 v[26:27], s[12:13], 0, v[0:1]
	v_mul_f32_e32 v29, 0x45800000, v28
	v_cndmask_b32_e64 v28, v28, v29, s[8:9]
	v_pk_mul_f32 v[14:15], v[14:15], v[28:29] op_sel_hi:[1,0]
	v_pk_mul_f32 v[16:17], v[16:17], v[28:29] op_sel_hi:[1,0]
	s_waitcnt vmcnt(0)
	v_pk_mul_f32 v[14:15], v[32:33], v[14:15]
	v_pk_mul_f32 v[16:17], v[34:35], v[16:17]
	global_store_dwordx4 v[24:25], v[14:17], off
	s_and_saveexec_b64 s[8:9], vcc
	s_cbranch_execz .LBB0_32
	s_mov_b32 s10, 0x800000
	v_readlane_b32 s12, v253, 5
	v_lshlrev_b64 v[20:21], 12, v[20:21]
	v_readlane_b32 s18, v253, 11
	v_readlane_b32 s19, v253, 12
	v_readlane_b32 s13, v253, 6
	v_readlane_b32 s14, v253, 7
	v_lshl_add_u64 v[20:21], s[18:19], 0, v[20:21]
	s_mov_b32 s19, 0x400000
	v_lshl_add_u64 v[20:21], v[20:21], 0, v[0:1]
	v_readlane_b32 s15, v253, 8
	v_readlane_b32 s16, v253, 9
	v_readlane_b32 s17, v253, 10
	v_fmamk_f32 v24, v41, 0x3a800000, v219
	v_mul_f32_e32 v25, 0x4b800000, v24
	v_cmp_gt_f32_e32 vcc, s10, v24
	s_nop 1
	v_cndmask_b32_e32 v24, v24, v25, vcc
	v_rsq_f32_e32 v24, v24
	s_nop 0
	v_mul_f32_e32 v25, 0x45800000, v24
	v_cndmask_b32_e32 v24, v24, v25, vcc
	v_pk_mul_f32 v[28:29], v[2:3], v[24:25] op_sel_hi:[1,0]
	v_pk_mul_f32 v[24:25], v[4:5], v[24:25] op_sel_hi:[1,0]
	v_pk_mul_f32 v[14:15], v[32:33], v[28:29]
	v_pk_mul_f32 v[16:17], v[34:35], v[24:25]
	global_store_dwordx4 v[20:21], v[14:17], off
	s_or_b64 exec, exec, s[8:9]
	s_and_saveexec_b64 s[8:9], s[0:1]
	s_cbranch_execnz .LBB0_33

.LBB0_33:
	s_mov_b32 s0, 0x800000
	v_readlane_b32 s12, v253, 5
	v_readlane_b32 s18, v253, 11
	v_readlane_b32 s19, v253, 12
	v_readlane_b32 s13, v253, 6
	v_readlane_b32 s14, v253, 7
	v_readlane_b32 s15, v253, 8
	v_readlane_b32 s16, v253, 9
	v_readlane_b32 s17, v253, 10
	v_fmamk_f32 v20, v42, 0x3a800000, v219
	v_mul_f32_e32 v21, 0x4b800000, v20
	v_cmp_gt_f32_e32 vcc, s0, v20
	s_nop 1
	v_cndmask_b32_e32 v20, v20, v21, vcc
	v_rsq_f32_e32 v24, v20
	v_lshlrev_b64 v[20:21], 12, v[22:23]
	v_lshl_add_u64 v[20:21], s[18:19], 0, v[20:21]
	s_mov_b32 s19, 0x400000
	v_mul_f32_e32 v22, 0x45800000, v24
	v_cndmask_b32_e32 v22, v24, v22, vcc
	v_pk_mul_f32 v[24:25], v[6:7], v[22:23] op_sel_hi:[1,0]
	v_pk_mul_f32 v[22:23], v[8:9], v[22:23] op_sel_hi:[1,0]
	v_pk_mul_f32 v[14:15], v[32:33], v[24:25]
	v_pk_mul_f32 v[16:17], v[34:35], v[22:23]
	v_lshl_add_u64 v[20:21], v[20:21], 0, v[0:1]
	global_store_dwordx4 v[20:21], v[14:17], off
	s_or_b64 exec, exec, s[8:9]
	s_and_saveexec_b64 s[0:1], s[6:7]
	s_cbranch_execz .LBB0_22
.LBB0_34:
	s_mov_b32 s6, 0x800000
	v_readlane_b32 s8, v253, 5
	v_lshlrev_b64 v[18:19], 12, v[18:19]
	v_readlane_b32 s14, v253, 11
	v_readlane_b32 s15, v253, 12
	v_readlane_b32 s9, v253, 6
	v_readlane_b32 s10, v253, 7
	v_lshl_add_u64 v[18:19], s[14:15], 0, v[18:19]
	v_lshl_add_u64 v[18:19], v[18:19], 0, v[0:1]
	v_readlane_b32 s11, v253, 8
	v_readlane_b32 s12, v253, 9
	v_readlane_b32 s13, v253, 10
	v_fmamk_f32 v20, v43, 0x3a800000, v219
	v_mul_f32_e32 v21, 0x4b800000, v20
	v_cmp_gt_f32_e32 vcc, s6, v20
	s_nop 1
	v_cndmask_b32_e32 v20, v20, v21, vcc
	v_rsq_f32_e32 v20, v20
	s_nop 0
	v_mul_f32_e32 v21, 0x45800000, v20
	v_cndmask_b32_e32 v20, v20, v21, vcc
	v_pk_mul_f32 v[22:23], v[10:11], v[20:21] op_sel_hi:[1,0]
	v_pk_mul_f32 v[20:21], v[12:13], v[20:21] op_sel_hi:[1,0]
	v_pk_mul_f32 v[14:15], v[32:33], v[22:23]
	v_pk_mul_f32 v[16:17], v[34:35], v[20:21]
	global_store_dwordx4 v[18:19], v[14:17], off
	s_branch .LBB0_22

.LBB0_137:
	v_and_b32_e32 v0, 16, v36
	v_cmp_eq_u32_e32 vcc, 0, v0
	v_mov_b32_e32 v0, 0x11e00000
	v_mov_b32_e32 v26, 0xfe00000
	v_readlane_b32 s4, v254, 38
	v_cndmask_b32_e32 v0, v0, v26, vcc
	v_readlane_b32 s5, v254, 39
	v_ashrrev_i32_e32 v44, 5, v36
	v_ashrrev_i32_e32 v45, 31, v44
	v_lshl_add_u64 v[26:27], s[4:5], 0, v[0:1]
	v_and_b32_e32 v0, 0x3c0, v58
	v_lshlrev_b32_e32 v0, 1, v0
	v_lshl_add_u64 v[34:35], v[26:27], 0, v[0:1]
	v_lshlrev_b64 v[26:27], 11, v[44:45]
	v_lshl_add_u64 v[42:43], v[34:35], 0, v[26:27]
	global_load_dwordx4 v[26:29], v[42:43], off offset:16
	global_load_dwordx4 v[30:33], v[42:43], off
	v_readlane_b32 s66, v254, 10
	v_readlane_b32 s67, v254, 11
	s_nop 1
	v_lshl_add_u64 v[64:65], v[44:45], 2, s[66:67]
	global_load_dword v66, v[64:65], off
	v_add_u32_e32 v0, s8, v36
	s_mov_b32 s10, 0x80000
	v_ashrrev_i32_e32 v40, 5, v0
	v_cmp_gt_i32_e64 s[8:9], s10, v0
	v_ashrrev_i32_e32 v41, 31, v40
	v_readlane_b32 s6, v254, 40
	v_readlane_b32 s7, v254, 41
	s_and_saveexec_b64 s[4:5], s[8:9]
	s_cbranch_execz .LBB0_139
	v_lshlrev_b64 v[10:11], 11, v[40:41]
	v_lshl_add_u64 v[10:11], v[34:35], 0, v[10:11]
	global_load_dwordx4 v[22:25], v[10:11], off offset:16
	s_waitcnt lgkmcnt(0)
	global_load_dwordx4 v[10:13], v[10:11], off
	v_lshl_add_u64 v[64:65], v[40:41], 2, s[66:67]
	global_load_dword v67, v[64:65], off
.LBB0_139:
	s_or_b64 exec, exec, s[4:5]
	v_readlane_b32 s4, v254, 29
	s_nop 1
	v_add_u32_e32 v37, s4, v36
	v_ashrrev_i32_e32 v38, 5, v37
	v_cmp_gt_i32_e64 s[6:7], s10, v37
	v_ashrrev_i32_e32 v39, 31, v38
	s_and_saveexec_b64 s[4:5], s[6:7]
	s_cbranch_execz .LBB0_141
	v_lshlrev_b64 v[6:7], 11, v[38:39]
	v_lshl_add_u64 v[6:7], v[34:35], 0, v[6:7]
	global_load_dwordx4 v[18:21], v[6:7], off offset:16
	s_nop 0
	global_load_dwordx4 v[6:9], v[6:7], off
	v_lshl_add_u64 v[64:65], v[38:39], 2, s[66:67]
	global_load_dword v68, v[64:65], off
.LBB0_141:
	s_or_b64 exec, exec, s[4:5]
	v_readlane_b32 s4, v253, 51
	s_nop 1
	v_add_u32_e32 v36, s4, v36
	s_mov_b32 s4, 0x80000
	v_cmp_gt_i32_e32 vcc, s4, v36
	v_ashrrev_i32_e32 v36, 5, v36
	v_ashrrev_i32_e32 v37, 31, v36
	s_and_saveexec_b64 s[4:5], vcc
	s_cbranch_execz .LBB0_143
	s_waitcnt lgkmcnt(0)
	v_lshlrev_b64 v[2:3], 11, v[36:37]
	v_lshl_add_u64 v[2:3], v[34:35], 0, v[2:3]
	global_load_dwordx4 v[14:17], v[2:3], off offset:16
	s_nop 0
	global_load_dwordx4 v[2:5], v[2:3], off
	v_lshl_add_u64 v[64:65], v[36:37], 2, s[66:67]
	global_load_dword v69, v[64:65], off
.LBB0_143:
	s_or_b64 exec, exec, s[4:5]
	v_readlane_b32 s64, v254, 8
	v_readlane_b32 s66, v254, 10
	v_readlane_b32 s67, v254, 11
	s_waitcnt vmcnt(0)
	v_lshlrev_b32_e32 v50, 16, v30
	v_and_b32_e32 v51, 0xffff0000, v30
	v_lshlrev_b32_e32 v52, 16, v26
	v_and_b32_e32 v53, 0xffff0000, v26
	v_lshlrev_b32_e32 v30, 16, v31
	v_and_b32_e32 v31, 0xffff0000, v31
	v_lshlrev_b32_e32 v54, 16, v32
	v_and_b32_e32 v55, 0xffff0000, v32
	v_lshlrev_b32_e32 v60, 16, v28
	v_and_b32_e32 v61, 0xffff0000, v28
	v_lshlrev_b32_e32 v32, 16, v33
	v_and_b32_e32 v33, 0xffff0000, v33
	v_readlane_b32 s65, v254, 9
	v_readlane_b32 s68, v254, 12
	v_readlane_b32 s69, v254, 13
	v_readlane_b32 s70, v254, 14
	v_readlane_b32 s71, v254, 15
	v_readlane_b32 s72, v254, 16
	v_readlane_b32 s73, v254, 17
	v_readlane_b32 s74, v254, 18
	v_readlane_b32 s75, v254, 19
	v_readlane_b32 s76, v254, 20
	v_readlane_b32 s77, v254, 21
	v_readlane_b32 s78, v254, 22
	v_readlane_b32 s79, v254, 23
	v_cvt_f64_i32_e32 v[56:57], v66
	v_mul_f64 v[44:45], v[56:57], s[12:13]
	v_floor_f64_e32 v[44:45], v[44:45]
	v_fma_f64 v[44:45], v[56:57], s[12:13], -v[44:45]
	v_cvt_f32_f64_e32 v44, v[44:45]
	v_sin_f32_e32 v46, v44
	v_cos_f32_e32 v48, v44
	v_mul_f64 v[44:45], v[56:57], s[14:15]
	v_floor_f64_e32 v[44:45], v[44:45]
	v_fma_f64 v[44:45], v[56:57], s[14:15], -v[44:45]
	v_cvt_f32_f64_e32 v44, v[44:45]
	v_sin_f32_e32 v47, v44
	v_cos_f32_e32 v49, v44
	v_pk_mul_f32 v[44:45], v[46:47], v[52:53]
	v_pk_mul_f32 v[46:47], v[46:47], v[50:51]
	v_pk_fma_f32 v[44:45], v[48:49], v[50:51], v[44:45] neg_lo:[0,0,1] neg_hi:[0,0,1]
	v_pk_fma_f32 v[46:47], v[48:49], v[52:53], v[46:47]
	v_mul_f64 v[48:49], v[56:57], s[16:17]
	v_floor_f64_e32 v[48:49], v[48:49]
	v_mul_f64 v[52:53], v[56:57], s[18:19]
	v_fma_f64 v[48:49], v[56:57], s[16:17], -v[48:49]
	v_floor_f64_e32 v[52:53], v[52:53]
	v_cvt_f32_f64_e32 v26, v[48:49]
	v_fma_f64 v[52:53], v[56:57], s[18:19], -v[52:53]
	v_sin_f32_e32 v48, v26
	v_cos_f32_e32 v50, v26
	v_cvt_f32_f64_e32 v26, v[52:53]
	v_sin_f32_e32 v49, v26
	v_cos_f32_e32 v51, v26
	v_lshlrev_b32_e32 v52, 16, v27
	v_and_b32_e32 v53, 0xffff0000, v27
	v_pk_mul_f32 v[26:27], v[48:49], v[52:53]
	s_nop 0
	v_pk_fma_f32 v[26:27], v[50:51], v[30:31], v[26:27] neg_lo:[0,0,1] neg_hi:[0,0,1]
	v_pk_mul_f32 v[30:31], v[48:49], v[30:31]
	v_mul_f64 v[48:49], v[56:57], s[22:23]
	v_floor_f64_e32 v[48:49], v[48:49]
	v_fma_f64 v[48:49], v[56:57], s[22:23], -v[48:49]
	v_cvt_f32_f64_e32 v48, v[48:49]
	v_pk_fma_f32 v[30:31], v[50:51], v[52:53], v[30:31]
	v_sin_f32_e32 v50, v48
	v_cos_f32_e32 v52, v48
	v_mul_f64 v[48:49], v[56:57], s[24:25]
	v_floor_f64_e32 v[48:49], v[48:49]
	v_fma_f64 v[48:49], v[56:57], s[24:25], -v[48:49]
	v_cvt_f32_f64_e32 v48, v[48:49]
	v_sin_f32_e32 v51, v48
	v_cos_f32_e32 v53, v48
	v_pk_mul_f32 v[48:49], v[50:51], v[60:61]
	v_pk_mul_f32 v[50:51], v[50:51], v[54:55]
	v_pk_fma_f32 v[48:49], v[52:53], v[54:55], v[48:49] neg_lo:[0,0,1] neg_hi:[0,0,1]
	v_pk_fma_f32 v[50:51], v[52:53], v[60:61], v[50:51]
	v_mul_f64 v[52:53], v[56:57], s[26:27]
	v_floor_f64_e32 v[52:53], v[52:53]
	v_mul_f64 v[60:61], v[56:57], s[30:31]
	v_fma_f64 v[52:53], v[56:57], s[26:27], -v[52:53]
	v_floor_f64_e32 v[60:61], v[60:61]
	v_cvt_f32_f64_e32 v28, v[52:53]
	v_fma_f64 v[56:57], v[56:57], s[30:31], -v[60:61]
	v_sin_f32_e32 v54, v28
	v_cos_f32_e32 v52, v28
	v_cvt_f32_f64_e32 v28, v[56:57]
	v_sin_f32_e32 v55, v28
	v_cos_f32_e32 v53, v28
	v_lshlrev_b32_e32 v28, 16, v29
	v_and_b32_e32 v29, 0xffff0000, v29
	v_pk_mul_f32 v[56:57], v[54:55], v[28:29]
	s_nop 0
	v_pk_fma_f32 v[56:57], v[52:53], v[32:33], v[56:57] neg_lo:[0,0,1] neg_hi:[0,0,1]
	v_pk_mul_f32 v[32:33], v[54:55], v[32:33]
	s_nop 0
	v_pk_fma_f32 v[32:33], v[52:53], v[28:29], v[32:33]
	v_cvt_pk_bf16_f32 v28, v44, v45
	v_cvt_pk_bf16_f32 v29, v26, v27
	v_cvt_pk_bf16_f32 v45, v30, v31
	v_cvt_pk_bf16_f32 v30, v48, v49
	v_cvt_pk_bf16_f32 v31, v56, v57
	v_cvt_pk_bf16_f32 v44, v46, v47
	v_cvt_pk_bf16_f32 v46, v50, v51
	v_cvt_pk_bf16_f32 v47, v32, v33
	global_store_dwordx4 v[42:43], v[28:31], off
	global_store_dwordx4 v[42:43], v[44:47], off offset:16
	s_and_saveexec_b64 s[4:5], s[8:9]
	s_cbranch_execz .LBB0_146
	v_readlane_b32 s64, v254, 8
	v_readlane_b32 s66, v254, 10
	v_readlane_b32 s67, v254, 11
	v_lshlrev_b64 v[42:43], 11, v[40:41]
	v_lshlrev_b32_e32 v44, 16, v22
	v_lshlrev_b32_e32 v40, 16, v10
	v_and_b32_e32 v41, 0xffff0000, v10
	v_and_b32_e32 v45, 0xffff0000, v22
	v_lshlrev_b32_e32 v46, 16, v23
	v_and_b32_e32 v47, 0xffff0000, v23
	v_lshlrev_b32_e32 v50, 16, v24
	v_and_b32_e32 v51, 0xffff0000, v24
	v_readlane_b32 s65, v254, 9
	v_readlane_b32 s68, v254, 12
	v_readlane_b32 s69, v254, 13
	v_readlane_b32 s70, v254, 14
	v_readlane_b32 s71, v254, 15
	v_readlane_b32 s72, v254, 16
	v_readlane_b32 s73, v254, 17
	v_readlane_b32 s74, v254, 18
	v_readlane_b32 s75, v254, 19
	v_readlane_b32 s76, v254, 20
	v_readlane_b32 s77, v254, 21
	v_readlane_b32 s78, v254, 22
	v_readlane_b32 s79, v254, 23
	v_cvt_f64_i32_e32 v[30:31], v67
	v_mul_f64 v[26:27], v[30:31], s[12:13]
	v_floor_f64_e32 v[26:27], v[26:27]
	v_fma_f64 v[26:27], v[30:31], s[12:13], -v[26:27]
	v_cvt_f32_f64_e32 v26, v[26:27]
	v_sin_f32_e32 v28, v26
	v_cos_f32_e32 v32, v26
	v_mul_f64 v[26:27], v[30:31], s[14:15]
	v_floor_f64_e32 v[26:27], v[26:27]
	v_fma_f64 v[26:27], v[30:31], s[14:15], -v[26:27]
	v_cvt_f32_f64_e32 v26, v[26:27]
	v_sin_f32_e32 v29, v26
	v_cos_f32_e32 v33, v26
	v_pk_mul_f32 v[26:27], v[28:29], v[44:45]
	v_pk_mul_f32 v[28:29], v[28:29], v[40:41]
	v_pk_fma_f32 v[26:27], v[32:33], v[40:41], v[26:27] neg_lo:[0,0,1] neg_hi:[0,0,1]
	v_pk_fma_f32 v[28:29], v[32:33], v[44:45], v[28:29]
	v_mul_f64 v[32:33], v[30:31], s[16:17]
	v_mul_f64 v[44:45], v[30:31], s[18:19]
	v_floor_f64_e32 v[32:33], v[32:33]
	v_floor_f64_e32 v[44:45], v[44:45]
	v_fma_f64 v[32:33], v[30:31], s[16:17], -v[32:33]
	v_fma_f64 v[44:45], v[30:31], s[18:19], -v[44:45]
	v_cvt_f32_f64_e32 v33, v[32:33]
	v_cvt_f32_f64_e32 v41, v[44:45]
	v_sin_f32_e32 v32, v33
	v_cos_f32_e32 v40, v33
	v_sin_f32_e32 v33, v41
	v_cos_f32_e32 v41, v41
	v_lshlrev_b32_e32 v44, 16, v11
	v_and_b32_e32 v45, 0xffff0000, v11
	v_pk_mul_f32 v[48:49], v[32:33], v[46:47]
	v_pk_mul_f32 v[32:33], v[32:33], v[44:45]
	v_pk_fma_f32 v[48:49], v[40:41], v[44:45], v[48:49] neg_lo:[0,0,1] neg_hi:[0,0,1]
	v_pk_fma_f32 v[32:33], v[40:41], v[46:47], v[32:33]
	v_mul_f64 v[40:41], v[30:31], s[22:23]
	v_mul_f64 v[46:47], v[30:31], s[24:25]
	v_floor_f64_e32 v[40:41], v[40:41]
	v_floor_f64_e32 v[46:47], v[46:47]
	v_fma_f64 v[40:41], v[30:31], s[22:23], -v[40:41]
	v_fma_f64 v[46:47], v[30:31], s[24:25], -v[46:47]
	v_cvt_f32_f64_e32 v41, v[40:41]
	v_cvt_f32_f64_e32 v45, v[46:47]
	v_sin_f32_e32 v40, v41
	v_cos_f32_e32 v44, v41
	v_sin_f32_e32 v41, v45
	v_cos_f32_e32 v45, v45
	s_waitcnt lgkmcnt(0)
	v_lshlrev_b32_e32 v46, 16, v12
	v_and_b32_e32 v47, 0xffff0000, v12
	v_pk_mul_f32 v[52:53], v[40:41], v[50:51]
	v_pk_mul_f32 v[40:41], v[40:41], v[46:47]
	v_pk_fma_f32 v[52:53], v[44:45], v[46:47], v[52:53] neg_lo:[0,0,1] neg_hi:[0,0,1]
	v_pk_fma_f32 v[40:41], v[44:45], v[50:51], v[40:41]
	v_mul_f64 v[44:45], v[30:31], s[26:27]
	v_mul_f64 v[50:51], v[30:31], s[30:31]
	v_floor_f64_e32 v[44:45], v[44:45]
	v_floor_f64_e32 v[50:51], v[50:51]
	v_fma_f64 v[44:45], v[30:31], s[26:27], -v[44:45]
	v_fma_f64 v[30:31], v[30:31], s[30:31], -v[50:51]
	v_cvt_f32_f64_e32 v45, v[44:45]
	v_cvt_f32_f64_e32 v30, v[30:31]
	v_sin_f32_e32 v44, v45
	v_cos_f32_e32 v46, v45
	v_sin_f32_e32 v45, v30
	v_cos_f32_e32 v47, v30
	v_lshlrev_b32_e32 v50, 16, v25
	v_and_b32_e32 v51, 0xffff0000, v25
	v_lshlrev_b32_e32 v30, 16, v13
	v_and_b32_e32 v31, 0xffff0000, v13
	v_pk_mul_f32 v[54:55], v[44:45], v[50:51]
	s_nop 0
	v_pk_fma_f32 v[54:55], v[46:47], v[30:31], v[54:55] neg_lo:[0,0,1] neg_hi:[0,0,1]
	v_pk_mul_f32 v[30:31], v[44:45], v[30:31]
	s_nop 0
	v_pk_fma_f32 v[44:45], v[46:47], v[50:51], v[30:31]
	v_cvt_pk_bf16_f32 v30, v26, v27
	v_cvt_pk_bf16_f32 v26, v28, v29
	v_cvt_pk_bf16_f32 v31, v48, v49
	v_cvt_pk_bf16_f32 v27, v32, v33
	v_cvt_pk_bf16_f32 v32, v52, v53
	v_cvt_pk_bf16_f32 v28, v40, v41
	v_cvt_pk_bf16_f32 v33, v54, v55
	v_lshl_add_u64 v[40:41], v[34:35], 0, v[42:43]
	v_cvt_pk_bf16_f32 v29, v44, v45
	global_store_dwordx4 v[40:41], v[30:33], off
	global_store_dwordx4 v[40:41], v[26:29], off offset:16
	s_or_b64 exec, exec, s[4:5]
	s_and_saveexec_b64 s[4:5], s[6:7]
	s_cbranch_execnz .LBB0_147

.LBB0_147:
	v_readlane_b32 s64, v254, 8
	v_readlane_b32 s66, v254, 10
	v_readlane_b32 s67, v254, 11
	v_lshlrev_b64 v[40:41], 11, v[38:39]
	v_lshlrev_b32_e32 v42, 16, v18
	v_lshlrev_b32_e32 v38, 16, v6
	v_and_b32_e32 v39, 0xffff0000, v6
	v_and_b32_e32 v43, 0xffff0000, v18
	v_lshlrev_b32_e32 v44, 16, v19
	v_and_b32_e32 v45, 0xffff0000, v19
	v_lshlrev_b32_e32 v48, 16, v20
	v_and_b32_e32 v49, 0xffff0000, v20
	v_readlane_b32 s65, v254, 9
	v_readlane_b32 s68, v254, 12
	v_readlane_b32 s69, v254, 13
	v_readlane_b32 s70, v254, 14
	v_readlane_b32 s71, v254, 15
	v_readlane_b32 s72, v254, 16
	v_readlane_b32 s73, v254, 17
	v_readlane_b32 s74, v254, 18
	v_readlane_b32 s75, v254, 19
	v_readlane_b32 s76, v254, 20
	v_readlane_b32 s77, v254, 21
	v_readlane_b32 s78, v254, 22
	v_readlane_b32 s79, v254, 23
	v_cvt_f64_i32_e32 v[30:31], v68
	v_mul_f64 v[26:27], v[30:31], s[12:13]
	v_floor_f64_e32 v[26:27], v[26:27]
	v_fma_f64 v[26:27], v[30:31], s[12:13], -v[26:27]
	v_cvt_f32_f64_e32 v26, v[26:27]
	v_sin_f32_e32 v28, v26
	v_cos_f32_e32 v32, v26
	v_mul_f64 v[26:27], v[30:31], s[14:15]
	v_floor_f64_e32 v[26:27], v[26:27]
	v_fma_f64 v[26:27], v[30:31], s[14:15], -v[26:27]
	v_cvt_f32_f64_e32 v26, v[26:27]
	v_sin_f32_e32 v29, v26
	v_cos_f32_e32 v33, v26
	v_pk_mul_f32 v[26:27], v[28:29], v[42:43]
	v_pk_mul_f32 v[28:29], v[28:29], v[38:39]
	v_pk_fma_f32 v[26:27], v[32:33], v[38:39], v[26:27] neg_lo:[0,0,1] neg_hi:[0,0,1]
	v_pk_fma_f32 v[28:29], v[32:33], v[42:43], v[28:29]
	v_mul_f64 v[32:33], v[30:31], s[16:17]
	v_mul_f64 v[42:43], v[30:31], s[18:19]
	v_floor_f64_e32 v[32:33], v[32:33]
	v_floor_f64_e32 v[42:43], v[42:43]
	v_fma_f64 v[32:33], v[30:31], s[16:17], -v[32:33]
	v_fma_f64 v[42:43], v[30:31], s[18:19], -v[42:43]
	v_cvt_f32_f64_e32 v33, v[32:33]
	v_cvt_f32_f64_e32 v39, v[42:43]
	v_sin_f32_e32 v32, v33
	v_cos_f32_e32 v38, v33
	v_sin_f32_e32 v33, v39
	v_cos_f32_e32 v39, v39
	v_lshlrev_b32_e32 v42, 16, v7
	v_and_b32_e32 v43, 0xffff0000, v7
	v_pk_mul_f32 v[46:47], v[32:33], v[44:45]
	v_pk_mul_f32 v[32:33], v[32:33], v[42:43]
	v_pk_fma_f32 v[46:47], v[38:39], v[42:43], v[46:47] neg_lo:[0,0,1] neg_hi:[0,0,1]
	v_pk_fma_f32 v[32:33], v[38:39], v[44:45], v[32:33]
	v_mul_f64 v[38:39], v[30:31], s[22:23]
	v_mul_f64 v[44:45], v[30:31], s[24:25]
	v_floor_f64_e32 v[38:39], v[38:39]
	v_floor_f64_e32 v[44:45], v[44:45]
	v_fma_f64 v[38:39], v[30:31], s[22:23], -v[38:39]
	v_fma_f64 v[44:45], v[30:31], s[24:25], -v[44:45]
	v_cvt_f32_f64_e32 v39, v[38:39]
	v_cvt_f32_f64_e32 v43, v[44:45]
	v_sin_f32_e32 v38, v39
	v_cos_f32_e32 v42, v39
	v_sin_f32_e32 v39, v43
	v_cos_f32_e32 v43, v43
	v_lshlrev_b32_e32 v44, 16, v8
	v_and_b32_e32 v45, 0xffff0000, v8
	v_pk_mul_f32 v[50:51], v[38:39], v[48:49]
	v_pk_mul_f32 v[38:39], v[38:39], v[44:45]
	v_pk_fma_f32 v[50:51], v[42:43], v[44:45], v[50:51] neg_lo:[0,0,1] neg_hi:[0,0,1]
	v_pk_fma_f32 v[38:39], v[42:43], v[48:49], v[38:39]
	v_mul_f64 v[42:43], v[30:31], s[26:27]
	v_mul_f64 v[48:49], v[30:31], s[30:31]
	v_floor_f64_e32 v[42:43], v[42:43]
	v_floor_f64_e32 v[48:49], v[48:49]
	v_fma_f64 v[42:43], v[30:31], s[26:27], -v[42:43]
	v_fma_f64 v[30:31], v[30:31], s[30:31], -v[48:49]
	v_cvt_f32_f64_e32 v43, v[42:43]
	v_cvt_f32_f64_e32 v30, v[30:31]
	v_sin_f32_e32 v42, v43
	v_cos_f32_e32 v44, v43
	v_sin_f32_e32 v43, v30
	v_cos_f32_e32 v45, v30
	v_lshlrev_b32_e32 v48, 16, v21
	v_and_b32_e32 v49, 0xffff0000, v21
	v_lshlrev_b32_e32 v30, 16, v9
	v_and_b32_e32 v31, 0xffff0000, v9
	v_pk_mul_f32 v[52:53], v[42:43], v[48:49]
	s_nop 0
	v_pk_fma_f32 v[52:53], v[44:45], v[30:31], v[52:53] neg_lo:[0,0,1] neg_hi:[0,0,1]
	v_pk_mul_f32 v[30:31], v[42:43], v[30:31]
	s_nop 0
	v_pk_fma_f32 v[42:43], v[44:45], v[48:49], v[30:31]
	v_cvt_pk_bf16_f32 v30, v26, v27
	v_cvt_pk_bf16_f32 v26, v28, v29
	v_cvt_pk_bf16_f32 v31, v46, v47
	v_cvt_pk_bf16_f32 v27, v32, v33
	v_cvt_pk_bf16_f32 v32, v50, v51
	v_cvt_pk_bf16_f32 v28, v38, v39
	v_cvt_pk_bf16_f32 v33, v52, v53
	v_lshl_add_u64 v[38:39], v[34:35], 0, v[40:41]
	v_cvt_pk_bf16_f32 v29, v42, v43
	global_store_dwordx4 v[38:39], v[30:33], off
	global_store_dwordx4 v[38:39], v[26:29], off offset:16
	s_or_b64 exec, exec, s[4:5]
	s_and_saveexec_b64 s[4:5], vcc
	s_cbranch_execz .LBB0_136
.LBB0_148:
	v_readlane_b32 s64, v254, 8
	v_readlane_b32 s66, v254, 10
	v_readlane_b32 s67, v254, 11
	v_lshlrev_b64 v[38:39], 11, v[36:37]
	v_lshlrev_b32_e32 v40, 16, v14
	s_waitcnt lgkmcnt(0)
	v_lshlrev_b32_e32 v36, 16, v2
	v_and_b32_e32 v37, 0xffff0000, v2
	v_and_b32_e32 v41, 0xffff0000, v14
	v_lshlrev_b32_e32 v42, 16, v15
	v_and_b32_e32 v43, 0xffff0000, v15
	v_lshlrev_b32_e32 v46, 16, v16
	v_and_b32_e32 v47, 0xffff0000, v16
	v_lshl_add_u64 v[34:35], v[34:35], 0, v[38:39]
	v_readlane_b32 s65, v254, 9
	v_readlane_b32 s68, v254, 12
	v_readlane_b32 s69, v254, 13
	v_readlane_b32 s70, v254, 14
	v_readlane_b32 s71, v254, 15
	v_readlane_b32 s72, v254, 16
	v_readlane_b32 s73, v254, 17
	v_readlane_b32 s74, v254, 18
	v_readlane_b32 s75, v254, 19
	v_readlane_b32 s76, v254, 20
	v_readlane_b32 s77, v254, 21
	v_readlane_b32 s78, v254, 22
	v_readlane_b32 s79, v254, 23
	v_cvt_f64_i32_e32 v[30:31], v69
	v_mul_f64 v[26:27], v[30:31], s[12:13]
	v_floor_f64_e32 v[26:27], v[26:27]
	v_fma_f64 v[26:27], v[30:31], s[12:13], -v[26:27]
	v_cvt_f32_f64_e32 v26, v[26:27]
	v_sin_f32_e32 v28, v26
	v_cos_f32_e32 v32, v26
	v_mul_f64 v[26:27], v[30:31], s[14:15]
	v_floor_f64_e32 v[26:27], v[26:27]
	v_fma_f64 v[26:27], v[30:31], s[14:15], -v[26:27]
	v_cvt_f32_f64_e32 v26, v[26:27]
	v_sin_f32_e32 v29, v26
	v_cos_f32_e32 v33, v26
	v_pk_mul_f32 v[26:27], v[28:29], v[40:41]
	v_pk_mul_f32 v[28:29], v[28:29], v[36:37]
	v_pk_fma_f32 v[26:27], v[32:33], v[36:37], v[26:27] neg_lo:[0,0,1] neg_hi:[0,0,1]
	v_pk_fma_f32 v[28:29], v[32:33], v[40:41], v[28:29]
	v_mul_f64 v[32:33], v[30:31], s[16:17]
	v_mul_f64 v[40:41], v[30:31], s[18:19]
	v_floor_f64_e32 v[32:33], v[32:33]
	v_floor_f64_e32 v[40:41], v[40:41]
	v_fma_f64 v[32:33], v[30:31], s[16:17], -v[32:33]
	v_fma_f64 v[40:41], v[30:31], s[18:19], -v[40:41]
	v_cvt_f32_f64_e32 v33, v[32:33]
	v_cvt_f32_f64_e32 v37, v[40:41]
	v_sin_f32_e32 v32, v33
	v_cos_f32_e32 v36, v33
	v_sin_f32_e32 v33, v37
	v_cos_f32_e32 v37, v37
	v_lshlrev_b32_e32 v40, 16, v3
	v_and_b32_e32 v41, 0xffff0000, v3
	v_pk_mul_f32 v[44:45], v[32:33], v[42:43]
	v_pk_mul_f32 v[32:33], v[32:33], v[40:41]
	v_pk_fma_f32 v[44:45], v[36:37], v[40:41], v[44:45] neg_lo:[0,0,1] neg_hi:[0,0,1]
	v_pk_fma_f32 v[32:33], v[36:37], v[42:43], v[32:33]
	v_mul_f64 v[36:37], v[30:31], s[22:23]
	v_mul_f64 v[42:43], v[30:31], s[24:25]
	v_floor_f64_e32 v[36:37], v[36:37]
	v_floor_f64_e32 v[42:43], v[42:43]
	v_fma_f64 v[36:37], v[30:31], s[22:23], -v[36:37]
	v_fma_f64 v[42:43], v[30:31], s[24:25], -v[42:43]
	v_cvt_f32_f64_e32 v37, v[36:37]
	v_cvt_f32_f64_e32 v41, v[42:43]
	v_sin_f32_e32 v36, v37
	v_cos_f32_e32 v40, v37
	v_sin_f32_e32 v37, v41
	v_cos_f32_e32 v41, v41
	v_lshlrev_b32_e32 v42, 16, v4
	v_and_b32_e32 v43, 0xffff0000, v4
	v_pk_mul_f32 v[48:49], v[36:37], v[46:47]
	v_pk_mul_f32 v[36:37], v[36:37], v[42:43]
	v_pk_fma_f32 v[48:49], v[40:41], v[42:43], v[48:49] neg_lo:[0,0,1] neg_hi:[0,0,1]
	v_pk_fma_f32 v[36:37], v[40:41], v[46:47], v[36:37]
	v_mul_f64 v[40:41], v[30:31], s[26:27]
	v_mul_f64 v[46:47], v[30:31], s[30:31]
	v_floor_f64_e32 v[40:41], v[40:41]
	v_floor_f64_e32 v[46:47], v[46:47]
	v_fma_f64 v[40:41], v[30:31], s[26:27], -v[40:41]
	v_fma_f64 v[30:31], v[30:31], s[30:31], -v[46:47]
	v_cvt_f32_f64_e32 v41, v[40:41]
	v_cvt_f32_f64_e32 v30, v[30:31]
	v_sin_f32_e32 v40, v41
	v_cos_f32_e32 v42, v41
	v_sin_f32_e32 v41, v30
	v_cos_f32_e32 v43, v30
	v_lshlrev_b32_e32 v46, 16, v17
	v_and_b32_e32 v47, 0xffff0000, v17
	v_lshlrev_b32_e32 v30, 16, v5
	v_and_b32_e32 v31, 0xffff0000, v5
	v_pk_mul_f32 v[50:51], v[40:41], v[46:47]
	s_nop 0
	v_pk_fma_f32 v[50:51], v[42:43], v[30:31], v[50:51] neg_lo:[0,0,1] neg_hi:[0,0,1]
	v_pk_mul_f32 v[30:31], v[40:41], v[30:31]
	s_nop 0
	v_pk_fma_f32 v[40:41], v[42:43], v[46:47], v[30:31]
	v_cvt_pk_bf16_f32 v30, v26, v27
	v_cvt_pk_bf16_f32 v31, v44, v45
	v_cvt_pk_bf16_f32 v27, v32, v33
	v_cvt_pk_bf16_f32 v32, v48, v49
	v_cvt_pk_bf16_f32 v33, v50, v51
	v_cvt_pk_bf16_f32 v26, v28, v29
	v_cvt_pk_bf16_f32 v28, v36, v37
	v_cvt_pk_bf16_f32 v29, v40, v41
	global_store_dwordx4 v[34:35], v[30:33], off
	global_store_dwordx4 v[34:35], v[26:29], off offset:16
	s_branch .LBB0_136

.LBB0_405:
	v_lshl_add_u32 v176, s51, 8, v139
	v_cndmask_b32_e64 v0, 0, 1, s[22:23]
	v_mov_b32_e32 v170, 1.0
	v_cmp_ne_u32_e64 s[0:1], 1, v0
	s_andn2_b64 vcc, exec, s[22:23]
	v_ashrrev_i32_e32 v177, 31, v176
	v_mov_b32_e32 v174, 1.0
	s_cbranch_vccnz .LBB0_407
	v_lshl_add_u64 v[148:149], v[176:177], 4, s[24:25]
	global_load_dword v190, v[148:149], off
	global_load_dword v191, v[148:149], off offset:256
	global_load_dword v192, v[148:149], off offset:512
	global_load_dword v193, v[148:149], off offset:768
	global_load_dword v194, v[148:149], off offset:2048
	global_load_dword v195, v[148:149], off offset:2304
	global_load_dword v196, v[148:149], off offset:2560
	global_load_dword v197, v[148:149], off offset:2816
	s_mov_b32 s8, 0x800000
	s_waitcnt vmcnt(0)
	v_fmamk_f32 v0, v190, 0x3b000000, v219
	v_mul_f32_e32 v146, 0x4b800000, v0
	v_cmp_gt_f32_e32 vcc, s8, v0
	s_nop 1
	v_cndmask_b32_e32 v0, v0, v146, vcc
	v_rsq_f32_e32 v0, v0
	s_nop 0
	v_mul_f32_e32 v146, 0x45800000, v0
	v_cndmask_b32_e32 v174, v0, v146, vcc
.LBB0_407:
	v_or_b32_e32 v172, 16, v176
	s_and_b64 vcc, exec, s[0:1]
	v_ashrrev_i32_e32 v173, 31, v172
	s_cbranch_vccnz .LBB0_409
	s_mov_b32 s8, 0x800000
	v_fmamk_f32 v0, v191, 0x3b000000, v219
	v_mul_f32_e32 v146, 0x4b800000, v0
	v_cmp_gt_f32_e32 vcc, s8, v0
	s_nop 1
	v_cndmask_b32_e32 v0, v0, v146, vcc
	v_rsq_f32_e32 v0, v0
	s_nop 0
	v_mul_f32_e32 v146, 0x45800000, v0
	v_cndmask_b32_e32 v170, v0, v146, vcc
.LBB0_409:
	v_or_b32_e32 v168, 32, v176
	v_mov_b32_e32 v158, 1.0
	s_and_b64 vcc, exec, s[0:1]
	v_ashrrev_i32_e32 v169, 31, v168
	v_mov_b32_e32 v166, 1.0
	s_cbranch_vccnz .LBB0_411
	s_mov_b32 s8, 0x800000
	v_fmamk_f32 v0, v192, 0x3b000000, v219
	v_mul_f32_e32 v146, 0x4b800000, v0
	v_cmp_gt_f32_e32 vcc, s8, v0
	s_nop 1
	v_cndmask_b32_e32 v0, v0, v146, vcc
	v_rsq_f32_e32 v0, v0
	s_nop 0
	v_mul_f32_e32 v146, 0x45800000, v0
	v_cndmask_b32_e32 v166, v0, v146, vcc
.LBB0_411:
	v_or_b32_e32 v164, 48, v176
	s_and_b64 vcc, exec, s[0:1]
	v_ashrrev_i32_e32 v165, 31, v164
	s_cbranch_vccnz .LBB0_413
	s_mov_b32 s8, 0x800000
	v_fmamk_f32 v0, v193, 0x3b000000, v219
	v_mul_f32_e32 v146, 0x4b800000, v0
	v_cmp_gt_f32_e32 vcc, s8, v0
	s_nop 1
	v_cndmask_b32_e32 v0, v0, v146, vcc
	v_rsq_f32_e32 v0, v0
	s_nop 0
	v_mul_f32_e32 v146, 0x45800000, v0
	v_cndmask_b32_e32 v158, v0, v146, vcc
.LBB0_413:
	v_add_u32_e32 v150, 0x80, v176
	v_mov_b32_e32 v152, 1.0
	s_and_b64 vcc, exec, s[0:1]
	v_ashrrev_i32_e32 v151, 31, v150
	v_mov_b32_e32 v156, 1.0
	s_cbranch_vccnz .LBB0_415
	s_mov_b32 s8, 0x800000
	v_fmamk_f32 v0, v194, 0x3b000000, v219
	v_mul_f32_e32 v146, 0x4b800000, v0
	v_cmp_gt_f32_e32 vcc, s8, v0
	s_nop 1
	v_cndmask_b32_e32 v0, v0, v146, vcc
	v_rsq_f32_e32 v0, v0
	s_nop 0
	v_mul_f32_e32 v146, 0x45800000, v0
	v_cndmask_b32_e32 v156, v0, v146, vcc
.LBB0_415:
	s_and_b64 vcc, exec, s[0:1]
	s_cbranch_vccnz .LBB0_417
	s_mov_b32 s8, 0x800000
	v_fmamk_f32 v0, v195, 0x3b000000, v219
	v_mul_f32_e32 v146, 0x4b800000, v0
	v_cmp_gt_f32_e32 vcc, s8, v0
	s_nop 1
	v_cndmask_b32_e32 v0, v0, v146, vcc
	v_rsq_f32_e32 v0, v0
	s_nop 0
	v_mul_f32_e32 v146, 0x45800000, v0
	v_cndmask_b32_e32 v152, v0, v146, vcc
.LBB0_417:
	v_mov_b32_e32 v146, 1.0
	s_and_b64 vcc, exec, s[0:1]
	v_mov_b32_e32 v148, 1.0
	s_cbranch_vccnz .LBB0_419
	s_mov_b32 s8, 0x800000
	v_fmamk_f32 v0, v196, 0x3b000000, v219
	v_mul_f32_e32 v148, 0x4b800000, v0
	v_cmp_gt_f32_e32 vcc, s8, v0
	s_nop 1
	v_cndmask_b32_e32 v0, v0, v148, vcc
	v_rsq_f32_e32 v0, v0
	s_nop 0
	v_mul_f32_e32 v148, 0x45800000, v0
	v_cndmask_b32_e32 v148, v0, v148, vcc
.LBB0_419:
	s_and_b64 vcc, exec, s[0:1]
	s_cbranch_vccnz .LBB0_421
	s_mov_b32 s0, 0x800000
	v_fmamk_f32 v0, v197, 0x3b000000, v219
	v_mul_f32_e32 v146, 0x4b800000, v0
	v_cmp_gt_f32_e32 vcc, s0, v0
	s_nop 1
	v_cndmask_b32_e32 v0, v0, v146, vcc
	v_rsq_f32_e32 v0, v0
	s_nop 0
	v_mul_f32_e32 v146, 0x45800000, v0
	v_cndmask_b32_e32 v146, v0, v146, vcc
